# convert phase: nt (streaming) hint on the read-once f32 weight loads
# speedup vs baseline: 1.0042x; 1.0042x over previous
;     const int k0 = 64 * kb;
;     float wv[32];
; #pragma unroll
;     for (int i = 0; i < 32; ++i) { const int kk = 2 * i + (lane >> 5); wv[i] = W[(size_t)(k0 + kk) * N + n0 + (lane & 31)]; }
; #pragma unroll
;     for (int i = 0; i < 32; ++i) { const int kk = 2 * i + (lane >> 5); scr[kk * 33 + (lane & 31)] = wv[i]; }
.Lcv_common1:
	s_add_u32 s0, s48, s43
	s_addc_u32 s1, s49, 0
	s_load_dwordx2 s[30:31], s[0:1], 0x0
	s_lshl_b32 s26, s27, 6
	s_mul_i32 s25, s26, s36
	s_lshl_b32 s43, s28, 2
	s_add_i32 s25, s25, s43
	s_add_i32 s51, s51, s25
	s_mul_i32 s25, s29, s37
	s_lshl_b32 s26, s26, 1
	s_add_i32 s25, s25, s26
	s_add_i32 s52, s52, s25
	s_add_u32 s34, s22, s52
	s_addc_u32 s35, s23, 0
	s_waitcnt lgkmcnt(0)
	s_add_u32 s30, s30, s51
	s_addc_u32 s31, s31, 0
	v_mad_u32_u24 v5, v1, s36, v2
	s_lshl_b32 s0, s36, 3
	global_load_dwordx4 v[8:11], v5, s[30:31] nt
	v_add_u32_e32 v5, s0, v5
	global_load_dwordx4 v[12:15], v5, s[30:31] nt
	v_add_u32_e32 v5, s0, v5
	global_load_dwordx4 v[16:19], v5, s[30:31] nt
	v_add_u32_e32 v5, s0, v5
	global_load_dwordx4 v[20:23], v5, s[30:31] nt
	v_add_u32_e32 v5, s0, v5
	global_load_dwordx4 v[24:27], v5, s[30:31] nt
	v_add_u32_e32 v5, s0, v5
	global_load_dwordx4 v[28:31], v5, s[30:31] nt
	v_add_u32_e32 v5, s0, v5
	global_load_dwordx4 v[32:35], v5, s[30:31] nt
	v_add_u32_e32 v5, s0, v5
	global_load_dwordx4 v[36:39], v5, s[30:31] nt
	s_waitcnt vmcnt(0)

;     const int k0 = 64 * kb;
;     float wv[32];
; #pragma unroll
;     for (int i = 0; i < 32; ++i) { const int kk = 2 * i + (lane >> 5); wv[i] = W[(size_t)(k0 + kk) * N + n0 + (lane & 31)]; }
; #pragma unroll
;     for (int i = 0; i < 32; ++i) { const int kk = 2 * i + (lane >> 5); scr[kk * 33 + (lane & 31)] = wv[i]; }
.Lcv_common2:
	s_add_u32 s0, s48, s43
	s_addc_u32 s1, s49, 0
	s_load_dwordx2 s[30:31], s[0:1], 0x0
	s_lshl_b32 s26, s27, 6
	s_mul_i32 s25, s26, s36
	s_lshl_b32 s43, s28, 2
	s_add_i32 s25, s25, s43
	s_add_i32 s51, s51, s25
	s_mul_i32 s25, s29, s37
	s_lshl_b32 s26, s26, 1
	s_add_i32 s25, s25, s26
	s_add_i32 s52, s52, s25
	s_add_u32 s34, s22, s52
	s_addc_u32 s35, s23, 0
	s_waitcnt lgkmcnt(0)
	s_add_u32 s30, s30, s51
	s_addc_u32 s31, s31, 0
	v_mad_u32_u24 v5, v1, s36, v2
	s_lshl_b32 s0, s36, 3
	global_load_dwordx4 v[8:11], v5, s[30:31] nt
	v_add_u32_e32 v5, s0, v5
	global_load_dwordx4 v[12:15], v5, s[30:31] nt
	v_add_u32_e32 v5, s0, v5
	global_load_dwordx4 v[16:19], v5, s[30:31] nt
	v_add_u32_e32 v5, s0, v5
	global_load_dwordx4 v[20:23], v5, s[30:31] nt
	v_add_u32_e32 v5, s0, v5
	global_load_dwordx4 v[24:27], v5, s[30:31] nt
	v_add_u32_e32 v5, s0, v5
	global_load_dwordx4 v[28:31], v5, s[30:31] nt
	v_add_u32_e32 v5, s0, v5
	global_load_dwordx4 v[32:35], v5, s[30:31] nt
	v_add_u32_e32 v5, s0, v5
	global_load_dwordx4 v[36:39], v5, s[30:31] nt
